# plus: s_setprio 1 moved before each K-loop barrier and the redundant post-barrier lgkmcnt(0) dropped, so the first MFMA issues right at barrier release
# baseline (speedup 1.0000x reference)
.LBB0_222:
	s_waitcnt lgkmcnt(0)
	ds_read_b128 v[50:53], v188
	ds_read_b128 v[54:57], v188 offset:1024
	ds_read_b128 v[58:61], v188 offset:2048
	ds_read_b128 v[62:65], v188 offset:3072
	ds_read_b128 v[174:177], v189
	ds_read_b128 v[178:181], v189 offset:1024
	ds_read_b128 v[182:185], v189 offset:2048
	ds_read_b128 v[194:197], v189 offset:3072
	s_add_u32 s0, s6, 0xfffc0080
	s_addc_u32 s1, s7, -1
	s_cmp_eq_u32 s18, 12
	s_cselect_b32 s1, s2, s1
	s_cselect_b32 s0, s3, s0
	s_cselect_b32 s9, s11, s15
	s_cselect_b32 s8, s12, s13
	v_lshl_add_u64 v[230:231], s[6:7], 0, v[166:167]
	s_add_i32 m0, s21, 0xc000
	ds_read_b128 v[198:201], v190
	ds_read_b128 v[202:205], v190 offset:1024
	ds_read_b128 v[206:209], v190 offset:2048
	ds_read_b128 v[210:213], v190 offset:3072
	ds_read_b128 v[214:217], v190 offset:4096
	ds_read_b128 v[218:221], v190 offset:5120
	ds_read_b128 v[222:225], v190 offset:6144
	ds_read_b128 v[226:229], v190 offset:7168
	global_load_lds_dwordx4 v[230:231], off
	v_lshl_add_u64 v[230:231], s[6:7], 0, v[168:169]
	s_add_i32 m0, s21, 0xe000
	s_nop 0
	global_load_lds_dwordx4 v[230:231], off
	s_waitcnt vmcnt(8)
	s_waitcnt lgkmcnt(0)
	s_setprio 1
	s_barrier
	v_mfma_f32_16x16x32_bf16 v[142:145], v[50:53], v[198:201], v[142:145]
	v_mfma_f32_16x16x32_bf16 v[138:141], v[58:61], v[198:201], v[138:141]
	v_mfma_f32_16x16x32_bf16 v[126:129], v[50:53], v[206:209], v[126:129]
	v_mfma_f32_16x16x32_bf16 v[122:125], v[58:61], v[206:209], v[122:125]
	v_mfma_f32_16x16x32_bf16 v[110:113], v[50:53], v[214:217], v[110:113]
	v_mfma_f32_16x16x32_bf16 v[106:109], v[58:61], v[214:217], v[106:109]
	v_mfma_f32_16x16x32_bf16 v[94:97], v[50:53], v[222:225], v[94:97]
	v_mfma_f32_16x16x32_bf16 v[90:93], v[58:61], v[222:225], v[90:93]
	v_mfma_f32_16x16x32_bf16 v[142:145], v[54:57], v[202:205], v[142:145]
	v_mfma_f32_16x16x32_bf16 v[138:141], v[62:65], v[202:205], v[138:141]
	v_mfma_f32_16x16x32_bf16 v[126:129], v[54:57], v[210:213], v[126:129]
	v_mfma_f32_16x16x32_bf16 v[122:125], v[62:65], v[210:213], v[122:125]
	v_mfma_f32_16x16x32_bf16 v[110:113], v[54:57], v[218:221], v[110:113]
	v_mfma_f32_16x16x32_bf16 v[106:109], v[62:65], v[218:221], v[106:109]
	v_mfma_f32_16x16x32_bf16 v[94:97], v[54:57], v[226:229], v[94:97]
	v_mfma_f32_16x16x32_bf16 v[90:93], v[62:65], v[226:229], v[90:93]
	v_mfma_f32_16x16x32_bf16 v[134:137], v[174:177], v[198:201], v[134:137]
	v_mfma_f32_16x16x32_bf16 v[130:133], v[182:185], v[198:201], v[130:133]
	v_mfma_f32_16x16x32_bf16 v[118:121], v[174:177], v[206:209], v[118:121]
	v_mfma_f32_16x16x32_bf16 v[114:117], v[182:185], v[206:209], v[114:117]
	v_mfma_f32_16x16x32_bf16 v[102:105], v[174:177], v[214:217], v[102:105]
	v_mfma_f32_16x16x32_bf16 v[98:101], v[182:185], v[214:217], v[98:101]
	v_mfma_f32_16x16x32_bf16 v[86:89], v[174:177], v[222:225], v[86:89]
	v_mfma_f32_16x16x32_bf16 v[82:85], v[182:185], v[222:225], v[82:85]
	v_mfma_f32_16x16x32_bf16 v[134:137], v[178:181], v[202:205], v[134:137]
	v_mfma_f32_16x16x32_bf16 v[130:133], v[194:197], v[202:205], v[130:133]
	v_mfma_f32_16x16x32_bf16 v[118:121], v[178:181], v[210:213], v[118:121]
	v_mfma_f32_16x16x32_bf16 v[114:117], v[194:197], v[210:213], v[114:117]
	v_mfma_f32_16x16x32_bf16 v[102:105], v[178:181], v[218:221], v[102:105]
	v_mfma_f32_16x16x32_bf16 v[98:101], v[194:197], v[218:221], v[98:101]
	v_mfma_f32_16x16x32_bf16 v[86:89], v[178:181], v[226:229], v[86:89]
	v_mfma_f32_16x16x32_bf16 v[82:85], v[194:197], v[226:229], v[82:85]
	s_setprio 0
	s_barrier
	s_add_i32 s19, s77, s20
	v_lshl_add_u64 v[230:231], s[8:9], 0, v[154:155]
	s_mov_b32 m0, s19
	ds_read_b128 v[198:201], v190 offset:16384
	ds_read_b128 v[202:205], v190 offset:17408
	ds_read_b128 v[206:209], v190 offset:18432
	ds_read_b128 v[210:213], v190 offset:19456
	ds_read_b128 v[214:217], v190 offset:20480
	ds_read_b128 v[218:221], v190 offset:21504
	ds_read_b128 v[222:225], v190 offset:22528
	ds_read_b128 v[226:229], v190 offset:23552
	global_load_lds_dwordx4 v[230:231], off
	s_add_i32 m0, s19, 0x2000
	s_add_u32 s24, s8, 0x40000
	v_lshl_add_u64 v[232:233], s[8:9], 0, v[156:157]
	s_addc_u32 s25, s9, 0
	s_add_i32 s19, s96, s20
	global_load_lds_dwordx4 v[232:233], off
	v_lshl_add_u64 v[234:235], s[24:25], 0, v[154:155]
	s_mov_b32 m0, s19
	v_lshl_add_u64 v[236:237], s[0:1], 0, v[156:157]
	global_load_lds_dwordx4 v[234:235], off
	v_lshl_add_u64 v[234:235], s[24:25], 0, v[156:157]
	s_add_i32 m0, s19, 0x2000
	s_nop 0
	global_load_lds_dwordx4 v[234:235], off
	v_lshl_add_u64 v[234:235], s[0:1], 0, v[154:155]
	s_mov_b32 m0, s21
	s_nop 0
	global_load_lds_dwordx4 v[234:235], off
	s_mov_b32 m0, s22
	s_nop 0
	global_load_lds_dwordx4 v[236:237], off
	s_waitcnt vmcnt(8)
	s_waitcnt lgkmcnt(0)
	s_setprio 1
	s_barrier
	v_mfma_f32_16x16x32_bf16 v[78:81], v[50:53], v[198:201], v[78:81]
	v_mfma_f32_16x16x32_bf16 v[74:77], v[58:61], v[198:201], v[74:77]
	v_mfma_f32_16x16x32_bf16 v[46:49], v[50:53], v[206:209], v[46:49]
	v_mfma_f32_16x16x32_bf16 v[42:45], v[58:61], v[206:209], v[42:45]
	v_mfma_f32_16x16x32_bf16 v[30:33], v[50:53], v[214:217], v[30:33]
	v_mfma_f32_16x16x32_bf16 v[26:29], v[58:61], v[214:217], v[26:29]
	v_mfma_f32_16x16x32_bf16 v[14:17], v[50:53], v[222:225], v[14:17]
	v_mfma_f32_16x16x32_bf16 v[10:13], v[58:61], v[222:225], v[10:13]
	v_mfma_f32_16x16x32_bf16 v[78:81], v[54:57], v[202:205], v[78:81]
	v_mfma_f32_16x16x32_bf16 v[74:77], v[62:65], v[202:205], v[74:77]
	v_mfma_f32_16x16x32_bf16 v[46:49], v[54:57], v[210:213], v[46:49]
	v_mfma_f32_16x16x32_bf16 v[42:45], v[62:65], v[210:213], v[42:45]
	v_mfma_f32_16x16x32_bf16 v[30:33], v[54:57], v[218:221], v[30:33]
	v_mfma_f32_16x16x32_bf16 v[26:29], v[62:65], v[218:221], v[26:29]
	v_mfma_f32_16x16x32_bf16 v[14:17], v[54:57], v[226:229], v[14:17]
	v_mfma_f32_16x16x32_bf16 v[10:13], v[62:65], v[226:229], v[10:13]
	v_mfma_f32_16x16x32_bf16 v[38:41], v[174:177], v[206:209], v[38:41]
	v_mfma_f32_16x16x32_bf16 v[34:37], v[182:185], v[206:209], v[34:37]
	v_mfma_f32_16x16x32_bf16 v[22:25], v[174:177], v[214:217], v[22:25]
	v_mfma_f32_16x16x32_bf16 v[18:21], v[182:185], v[214:217], v[18:21]
	v_mfma_f32_16x16x32_bf16 v[6:9], v[174:177], v[222:225], v[6:9]
	v_mfma_f32_16x16x32_bf16 v[2:5], v[182:185], v[222:225], v[2:5]
	v_mfma_f32_16x16x32_bf16 v[50:53], v[174:177], v[198:201], v[70:73]
	v_mfma_f32_16x16x32_bf16 v[54:57], v[182:185], v[198:201], v[66:69]
	v_mfma_f32_16x16x32_bf16 v[38:41], v[178:181], v[210:213], v[38:41]
	v_mfma_f32_16x16x32_bf16 v[34:37], v[194:197], v[210:213], v[34:37]
	v_mfma_f32_16x16x32_bf16 v[22:25], v[178:181], v[218:221], v[22:25]
	v_mfma_f32_16x16x32_bf16 v[18:21], v[194:197], v[218:221], v[18:21]
	v_mfma_f32_16x16x32_bf16 v[6:9], v[178:181], v[226:229], v[6:9]
	v_mfma_f32_16x16x32_bf16 v[2:5], v[194:197], v[226:229], v[2:5]
	v_mfma_f32_16x16x32_bf16 v[50:53], v[178:181], v[202:205], v[50:53]
	v_mfma_f32_16x16x32_bf16 v[54:57], v[194:197], v[202:205], v[54:57]
	s_setprio 0
	s_barrier
	s_add_i32 s19, 0, 0x18000
	s_add_i32 s24, 0, 0x1c000
	v_add_u32_e32 v70, s19, v147
	v_add_u32_e32 v158, s24, v147
	ds_read_b128 v[58:61], v70
	ds_read_b128 v[62:65], v70 offset:1024
	ds_read_b128 v[66:69], v70 offset:2048
	ds_read_b128 v[70:73], v70 offset:3072
	ds_read_b128 v[174:177], v158
	ds_read_b128 v[178:181], v158 offset:1024
	ds_read_b128 v[182:185], v158 offset:2048
	ds_read_b128 v[194:197], v158 offset:3072
	s_add_u32 s0, s0, 0x40000
	s_addc_u32 s1, s1, 0
	s_mov_b32 m0, s23
	v_lshl_add_u64 v[238:239], s[0:1], 0, v[154:155]
	ds_read_b128 v[198:201], v190 offset:32768
	ds_read_b128 v[202:205], v190 offset:33792
	ds_read_b128 v[206:209], v190 offset:34816
	ds_read_b128 v[210:213], v190 offset:35840
	ds_read_b128 v[214:217], v190 offset:36864
	ds_read_b128 v[218:221], v190 offset:37888
	ds_read_b128 v[222:225], v190 offset:38912
	ds_read_b128 v[226:229], v190 offset:39936
	global_load_lds_dwordx4 v[238:239], off
	v_lshl_add_u64 v[238:239], s[0:1], 0, v[156:157]
	s_mov_b32 m0, s55
	s_nop 0
	global_load_lds_dwordx4 v[238:239], off
	s_waitcnt vmcnt(8)
	s_waitcnt lgkmcnt(0)
	s_setprio 1
	s_barrier
	v_mfma_f32_16x16x32_bf16 v[142:145], v[58:61], v[198:201], v[142:145]
	v_mfma_f32_16x16x32_bf16 v[138:141], v[66:69], v[198:201], v[138:141]
	v_mfma_f32_16x16x32_bf16 v[126:129], v[58:61], v[206:209], v[126:129]
	v_mfma_f32_16x16x32_bf16 v[122:125], v[66:69], v[206:209], v[122:125]
	v_mfma_f32_16x16x32_bf16 v[110:113], v[58:61], v[214:217], v[110:113]
	v_mfma_f32_16x16x32_bf16 v[106:109], v[66:69], v[214:217], v[106:109]
	v_mfma_f32_16x16x32_bf16 v[94:97], v[58:61], v[222:225], v[94:97]
	v_mfma_f32_16x16x32_bf16 v[90:93], v[66:69], v[222:225], v[90:93]
	v_mfma_f32_16x16x32_bf16 v[142:145], v[62:65], v[202:205], v[142:145]
	v_mfma_f32_16x16x32_bf16 v[138:141], v[70:73], v[202:205], v[138:141]
	v_mfma_f32_16x16x32_bf16 v[126:129], v[62:65], v[210:213], v[126:129]
	v_mfma_f32_16x16x32_bf16 v[122:125], v[70:73], v[210:213], v[122:125]
	v_mfma_f32_16x16x32_bf16 v[110:113], v[62:65], v[218:221], v[110:113]
	v_mfma_f32_16x16x32_bf16 v[106:109], v[70:73], v[218:221], v[106:109]
	v_mfma_f32_16x16x32_bf16 v[94:97], v[62:65], v[226:229], v[94:97]
	v_mfma_f32_16x16x32_bf16 v[90:93], v[70:73], v[226:229], v[90:93]
	v_mfma_f32_16x16x32_bf16 v[134:137], v[174:177], v[198:201], v[134:137]
	v_mfma_f32_16x16x32_bf16 v[130:133], v[182:185], v[198:201], v[130:133]
	v_mfma_f32_16x16x32_bf16 v[118:121], v[174:177], v[206:209], v[118:121]
	v_mfma_f32_16x16x32_bf16 v[114:117], v[182:185], v[206:209], v[114:117]
	v_mfma_f32_16x16x32_bf16 v[102:105], v[174:177], v[214:217], v[102:105]
	v_mfma_f32_16x16x32_bf16 v[98:101], v[182:185], v[214:217], v[98:101]
	v_mfma_f32_16x16x32_bf16 v[86:89], v[174:177], v[222:225], v[86:89]
	v_mfma_f32_16x16x32_bf16 v[82:85], v[182:185], v[222:225], v[82:85]
	v_mfma_f32_16x16x32_bf16 v[134:137], v[178:181], v[202:205], v[134:137]
	v_mfma_f32_16x16x32_bf16 v[130:133], v[194:197], v[202:205], v[130:133]
	v_mfma_f32_16x16x32_bf16 v[118:121], v[178:181], v[210:213], v[118:121]
	v_mfma_f32_16x16x32_bf16 v[114:117], v[194:197], v[210:213], v[114:117]
	v_mfma_f32_16x16x32_bf16 v[102:105], v[178:181], v[218:221], v[102:105]
	v_mfma_f32_16x16x32_bf16 v[98:101], v[194:197], v[218:221], v[98:101]
	v_mfma_f32_16x16x32_bf16 v[86:89], v[178:181], v[226:229], v[86:89]
	v_mfma_f32_16x16x32_bf16 v[82:85], v[194:197], v[226:229], v[82:85]
	s_setprio 0
	s_barrier
	s_add_i32 s0, s19, s20
	v_lshl_add_u64 v[230:231], v[230:231], 0, s[84:85]
	s_mov_b32 m0, s0
	ds_read_b128 v[198:201], v190 offset:49152
	ds_read_b128 v[202:205], v190 offset:50176
	ds_read_b128 v[206:209], v190 offset:51200
	ds_read_b128 v[210:213], v190 offset:52224
	ds_read_b128 v[214:217], v190 offset:53248
	ds_read_b128 v[218:221], v190 offset:54272
	ds_read_b128 v[222:225], v190 offset:55296
	ds_read_b128 v[226:229], v190 offset:56320
	global_load_lds_dwordx4 v[230:231], off
	s_add_i32 m0, s0, 0x2000
	s_add_u32 s0, s8, 0x40080
	v_lshl_add_u64 v[230:231], v[232:233], 0, s[84:85]
	s_addc_u32 s1, s9, 0
	s_add_i32 s8, s24, s20
	global_load_lds_dwordx4 v[230:231], off
	v_lshl_add_u64 v[230:231], s[0:1], 0, v[154:155]
	s_mov_b32 m0, s8
	s_nop 0
	global_load_lds_dwordx4 v[230:231], off
	v_lshl_add_u64 v[230:231], s[0:1], 0, v[156:157]
	s_add_i32 m0, s8, 0x2000
	s_nop 0
	global_load_lds_dwordx4 v[230:231], off
	v_lshl_add_u64 v[230:231], v[234:235], 0, s[84:85]
	s_mov_b32 m0, s67
	s_nop 0
	global_load_lds_dwordx4 v[230:231], off
	v_lshl_add_u64 v[230:231], v[236:237], 0, s[84:85]
	s_mov_b32 m0, s72
	s_nop 0
	global_load_lds_dwordx4 v[230:231], off
	s_waitcnt vmcnt(8)
	s_waitcnt lgkmcnt(0)
	s_setprio 1
	s_barrier
	v_mfma_f32_16x16x32_bf16 v[78:81], v[58:61], v[198:201], v[78:81]
	v_mfma_f32_16x16x32_bf16 v[74:77], v[66:69], v[198:201], v[74:77]
	v_mfma_f32_16x16x32_bf16 v[46:49], v[58:61], v[206:209], v[46:49]
	v_mfma_f32_16x16x32_bf16 v[42:45], v[66:69], v[206:209], v[42:45]
	v_mfma_f32_16x16x32_bf16 v[30:33], v[58:61], v[214:217], v[30:33]
	v_mfma_f32_16x16x32_bf16 v[26:29], v[66:69], v[214:217], v[26:29]
	v_mfma_f32_16x16x32_bf16 v[14:17], v[58:61], v[222:225], v[14:17]
	v_mfma_f32_16x16x32_bf16 v[10:13], v[66:69], v[222:225], v[10:13]
	v_mfma_f32_16x16x32_bf16 v[78:81], v[62:65], v[202:205], v[78:81]
	v_mfma_f32_16x16x32_bf16 v[74:77], v[70:73], v[202:205], v[74:77]
	v_mfma_f32_16x16x32_bf16 v[46:49], v[62:65], v[210:213], v[46:49]
	v_mfma_f32_16x16x32_bf16 v[42:45], v[70:73], v[210:213], v[42:45]
	v_mfma_f32_16x16x32_bf16 v[30:33], v[62:65], v[218:221], v[30:33]
	v_mfma_f32_16x16x32_bf16 v[26:29], v[70:73], v[218:221], v[26:29]
	v_mfma_f32_16x16x32_bf16 v[14:17], v[62:65], v[226:229], v[14:17]
	v_mfma_f32_16x16x32_bf16 v[10:13], v[70:73], v[226:229], v[10:13]
	v_mfma_f32_16x16x32_bf16 v[50:53], v[174:177], v[198:201], v[50:53]
	v_mfma_f32_16x16x32_bf16 v[70:73], v[178:181], v[202:205], v[50:53]
	v_mfma_f32_16x16x32_bf16 v[50:53], v[182:185], v[198:201], v[54:57]
	v_mfma_f32_16x16x32_bf16 v[38:41], v[174:177], v[206:209], v[38:41]
	v_mfma_f32_16x16x32_bf16 v[34:37], v[182:185], v[206:209], v[34:37]
	v_mfma_f32_16x16x32_bf16 v[22:25], v[174:177], v[214:217], v[22:25]
	v_mfma_f32_16x16x32_bf16 v[18:21], v[182:185], v[214:217], v[18:21]
	v_mfma_f32_16x16x32_bf16 v[6:9], v[174:177], v[222:225], v[6:9]
	v_mfma_f32_16x16x32_bf16 v[2:5], v[182:185], v[222:225], v[2:5]
	v_mfma_f32_16x16x32_bf16 v[66:69], v[194:197], v[202:205], v[50:53]
	v_mfma_f32_16x16x32_bf16 v[38:41], v[178:181], v[210:213], v[38:41]
	v_mfma_f32_16x16x32_bf16 v[34:37], v[194:197], v[210:213], v[34:37]
	v_mfma_f32_16x16x32_bf16 v[22:25], v[178:181], v[218:221], v[22:25]
	v_mfma_f32_16x16x32_bf16 v[18:21], v[194:197], v[218:221], v[18:21]
	v_mfma_f32_16x16x32_bf16 v[6:9], v[178:181], v[226:229], v[6:9]
	v_mfma_f32_16x16x32_bf16 v[2:5], v[194:197], v[226:229], v[2:5]
	s_setprio 0
	s_barrier
	s_add_i32 s18, s18, 2
	s_add_u32 s6, s6, 0x100
	s_addc_u32 s7, s7, 0
	s_add_u32 s13, s13, 0x100
	s_addc_u32 s15, s15, 0
	s_cmp_gt_u32 s18, 13
	s_cbranch_scc0 .LBB0_222
	s_and_b64 vcc, exec, s[86:87]
	s_cbranch_vccz .LBB0_225
	s_barrier

.LBB0_1797:
	ds_read_b128 v[130:133], v157
	ds_read_b128 v[152:155], v157 offset:1024
	ds_read_b128 v[160:163], v157 offset:2048
	ds_read_b128 v[164:167], v157 offset:3072
	ds_read_b128 v[168:171], v158
	ds_read_b128 v[172:175], v158 offset:1024
	ds_read_b128 v[176:179], v158 offset:2048
	ds_read_b128 v[180:183], v158 offset:3072
	s_add_u32 s0, s66, 0xfffc0080
	s_addc_u32 s1, s67, -1
	s_cmp_eq_u32 s91, 12
	s_cselect_b32 s71, s59, s1
	s_cselect_b32 s70, s87, s0
	s_cselect_b32 s69, s57, s90
	s_cselect_b32 s68, s88, s89
	v_lshl_add_u64 v[216:217], s[66:67], 0, v[140:141]
	s_add_i32 m0, s73, 0xc000
	ds_read_b128 v[184:187], v159
	ds_read_b128 v[188:191], v159 offset:1024
	ds_read_b128 v[192:195], v159 offset:2048
	ds_read_b128 v[196:199], v159 offset:3072
	ds_read_b128 v[200:203], v159 offset:4096
	ds_read_b128 v[204:207], v159 offset:5120
	ds_read_b128 v[208:211], v159 offset:6144
	ds_read_b128 v[212:215], v159 offset:7168
	global_load_lds_dwordx4 v[216:217], off
	v_lshl_add_u64 v[216:217], s[66:67], 0, v[142:143]
	s_add_i32 m0, s73, 0xe000
	s_nop 0
	global_load_lds_dwordx4 v[216:217], off
	s_waitcnt vmcnt(8)
	s_waitcnt lgkmcnt(0)
	s_setprio 1
	s_barrier
	v_mfma_f32_16x16x32_bf16 v[126:129], v[130:133], v[184:187], v[126:129]
	v_mfma_f32_16x16x32_bf16 v[122:125], v[160:163], v[184:187], v[122:125]
	v_mfma_f32_16x16x32_bf16 v[114:117], v[130:133], v[192:195], v[114:117]
	v_mfma_f32_16x16x32_bf16 v[106:109], v[160:163], v[192:195], v[106:109]
	v_mfma_f32_16x16x32_bf16 v[94:97], v[130:133], v[200:203], v[94:97]
	v_mfma_f32_16x16x32_bf16 v[90:93], v[160:163], v[200:203], v[90:93]
	v_mfma_f32_16x16x32_bf16 v[82:85], v[130:133], v[208:211], v[82:85]
	v_mfma_f32_16x16x32_bf16 v[74:77], v[160:163], v[208:211], v[74:77]
	v_mfma_f32_16x16x32_bf16 v[126:129], v[152:155], v[188:191], v[126:129]
	v_mfma_f32_16x16x32_bf16 v[122:125], v[164:167], v[188:191], v[122:125]
	v_mfma_f32_16x16x32_bf16 v[114:117], v[152:155], v[196:199], v[114:117]
	v_mfma_f32_16x16x32_bf16 v[106:109], v[164:167], v[196:199], v[106:109]
	v_mfma_f32_16x16x32_bf16 v[94:97], v[152:155], v[204:207], v[94:97]
	v_mfma_f32_16x16x32_bf16 v[90:93], v[164:167], v[204:207], v[90:93]
	v_mfma_f32_16x16x32_bf16 v[82:85], v[152:155], v[212:215], v[82:85]
	v_mfma_f32_16x16x32_bf16 v[74:77], v[164:167], v[212:215], v[74:77]
	v_mfma_f32_16x16x32_bf16 v[118:121], v[168:171], v[184:187], v[118:121]
	v_mfma_f32_16x16x32_bf16 v[110:113], v[176:179], v[184:187], v[110:113]
	v_mfma_f32_16x16x32_bf16 v[102:105], v[168:171], v[192:195], v[102:105]
	v_mfma_f32_16x16x32_bf16 v[98:101], v[176:179], v[192:195], v[98:101]
	v_mfma_f32_16x16x32_bf16 v[86:89], v[168:171], v[200:203], v[86:89]
	v_mfma_f32_16x16x32_bf16 v[78:81], v[176:179], v[200:203], v[78:81]
	v_mfma_f32_16x16x32_bf16 v[70:73], v[168:171], v[208:211], v[70:73]
	v_mfma_f32_16x16x32_bf16 v[66:69], v[176:179], v[208:211], v[66:69]
	v_mfma_f32_16x16x32_bf16 v[118:121], v[172:175], v[188:191], v[118:121]
	v_mfma_f32_16x16x32_bf16 v[110:113], v[180:183], v[188:191], v[110:113]
	v_mfma_f32_16x16x32_bf16 v[102:105], v[172:175], v[196:199], v[102:105]
	v_mfma_f32_16x16x32_bf16 v[98:101], v[180:183], v[196:199], v[98:101]
	v_mfma_f32_16x16x32_bf16 v[86:89], v[172:175], v[204:207], v[86:89]
	v_mfma_f32_16x16x32_bf16 v[78:81], v[180:183], v[204:207], v[78:81]
	v_mfma_f32_16x16x32_bf16 v[70:73], v[172:175], v[212:215], v[70:73]
	v_mfma_f32_16x16x32_bf16 v[66:69], v[180:183], v[212:215], v[66:69]
	s_setprio 0
	s_barrier
	s_add_i32 s0, s85, s43
	v_lshl_add_u64 v[216:217], s[68:69], 0, v[136:137]
	s_mov_b32 m0, s0
	ds_read_b128 v[184:187], v159 offset:16384
	ds_read_b128 v[188:191], v159 offset:17408
	ds_read_b128 v[192:195], v159 offset:18432
	ds_read_b128 v[196:199], v159 offset:19456
	ds_read_b128 v[200:203], v159 offset:20480
	ds_read_b128 v[204:207], v159 offset:21504
	ds_read_b128 v[208:211], v159 offset:22528
	ds_read_b128 v[212:215], v159 offset:23552
	global_load_lds_dwordx4 v[216:217], off
	s_add_i32 m0, s0, 0x2000
	s_add_u32 s0, s68, 0x40000
	v_lshl_add_u64 v[218:219], s[68:69], 0, v[138:139]
	s_addc_u32 s1, s69, 0
	s_add_i32 s2, s86, s43
	global_load_lds_dwordx4 v[218:219], off
	v_lshl_add_u64 v[220:221], s[0:1], 0, v[136:137]
	s_mov_b32 m0, s2
	v_lshl_add_u64 v[222:223], s[70:71], 0, v[138:139]
	global_load_lds_dwordx4 v[220:221], off
	v_lshl_add_u64 v[220:221], s[0:1], 0, v[138:139]
	s_add_i32 m0, s2, 0x2000
	s_nop 0
	global_load_lds_dwordx4 v[220:221], off
	v_lshl_add_u64 v[220:221], s[70:71], 0, v[136:137]
	s_mov_b32 m0, s73
	s_nop 0
	global_load_lds_dwordx4 v[220:221], off
	s_mov_b32 m0, s74
	s_nop 0
	global_load_lds_dwordx4 v[222:223], off
	s_waitcnt vmcnt(8)
	s_waitcnt lgkmcnt(0)
	s_setprio 1
	s_barrier
	v_mfma_f32_16x16x32_bf16 v[62:65], v[130:133], v[184:187], v[62:65]
	v_mfma_f32_16x16x32_bf16 v[58:61], v[160:163], v[184:187], v[58:61]
	v_mfma_f32_16x16x32_bf16 v[46:49], v[130:133], v[192:195], v[46:49]
	v_mfma_f32_16x16x32_bf16 v[42:45], v[160:163], v[192:195], v[42:45]
	v_mfma_f32_16x16x32_bf16 v[30:33], v[130:133], v[200:203], v[30:33]
	v_mfma_f32_16x16x32_bf16 v[26:29], v[160:163], v[200:203], v[26:29]
	v_mfma_f32_16x16x32_bf16 v[14:17], v[130:133], v[208:211], v[14:17]
	v_mfma_f32_16x16x32_bf16 v[10:13], v[160:163], v[208:211], v[10:13]
	v_mfma_f32_16x16x32_bf16 v[62:65], v[152:155], v[188:191], v[62:65]
	v_mfma_f32_16x16x32_bf16 v[58:61], v[164:167], v[188:191], v[58:61]
	v_mfma_f32_16x16x32_bf16 v[46:49], v[152:155], v[196:199], v[46:49]
	v_mfma_f32_16x16x32_bf16 v[42:45], v[164:167], v[196:199], v[42:45]
	v_mfma_f32_16x16x32_bf16 v[30:33], v[152:155], v[204:207], v[30:33]
	v_mfma_f32_16x16x32_bf16 v[26:29], v[164:167], v[204:207], v[26:29]
	v_mfma_f32_16x16x32_bf16 v[14:17], v[152:155], v[212:215], v[14:17]
	v_mfma_f32_16x16x32_bf16 v[10:13], v[164:167], v[212:215], v[10:13]
	v_mfma_f32_16x16x32_bf16 v[54:57], v[168:171], v[184:187], v[54:57]
	v_mfma_f32_16x16x32_bf16 v[50:53], v[176:179], v[184:187], v[50:53]
	v_mfma_f32_16x16x32_bf16 v[38:41], v[168:171], v[192:195], v[38:41]
	v_mfma_f32_16x16x32_bf16 v[34:37], v[176:179], v[192:195], v[34:37]
	v_mfma_f32_16x16x32_bf16 v[22:25], v[168:171], v[200:203], v[22:25]
	v_mfma_f32_16x16x32_bf16 v[18:21], v[176:179], v[200:203], v[18:21]
	v_mfma_f32_16x16x32_bf16 v[6:9], v[168:171], v[208:211], v[6:9]
	v_mfma_f32_16x16x32_bf16 v[2:5], v[176:179], v[208:211], v[2:5]
	v_mfma_f32_16x16x32_bf16 v[54:57], v[172:175], v[188:191], v[54:57]
	v_mfma_f32_16x16x32_bf16 v[50:53], v[180:183], v[188:191], v[50:53]
	v_mfma_f32_16x16x32_bf16 v[38:41], v[172:175], v[196:199], v[38:41]
	v_mfma_f32_16x16x32_bf16 v[34:37], v[180:183], v[196:199], v[34:37]
	v_mfma_f32_16x16x32_bf16 v[22:25], v[172:175], v[204:207], v[22:25]
	v_mfma_f32_16x16x32_bf16 v[18:21], v[180:183], v[204:207], v[18:21]
	v_mfma_f32_16x16x32_bf16 v[6:9], v[172:175], v[212:215], v[6:9]
	v_mfma_f32_16x16x32_bf16 v[2:5], v[180:183], v[212:215], v[2:5]
	s_setprio 0
	s_barrier
	s_add_i32 s2, 0, 0x18000
	s_add_i32 s3, 0, 0x1c000
	v_add_u32_e32 v164, s2, v147
	v_add_u32_e32 v180, s3, v147
	ds_read_b128 v[130:133], v164
	ds_read_b128 v[152:155], v164 offset:1024
	ds_read_b128 v[160:163], v164 offset:2048
	ds_read_b128 v[164:167], v164 offset:3072
	ds_read_b128 v[168:171], v180
	ds_read_b128 v[172:175], v180 offset:1024
	ds_read_b128 v[176:179], v180 offset:2048
	ds_read_b128 v[180:183], v180 offset:3072
	s_add_u32 s0, s70, 0x40000
	s_addc_u32 s1, s71, 0
	s_mov_b32 m0, s75
	v_lshl_add_u64 v[224:225], s[0:1], 0, v[136:137]
	ds_read_b128 v[184:187], v159 offset:32768
	ds_read_b128 v[188:191], v159 offset:33792
	ds_read_b128 v[192:195], v159 offset:34816
	ds_read_b128 v[196:199], v159 offset:35840
	ds_read_b128 v[200:203], v159 offset:36864
	ds_read_b128 v[204:207], v159 offset:37888
	ds_read_b128 v[208:211], v159 offset:38912
	ds_read_b128 v[212:215], v159 offset:39936
	global_load_lds_dwordx4 v[224:225], off
	v_lshl_add_u64 v[224:225], s[0:1], 0, v[138:139]
	s_mov_b32 m0, s76
	s_nop 0
	global_load_lds_dwordx4 v[224:225], off
	s_waitcnt vmcnt(8)
	s_waitcnt lgkmcnt(0)
	s_setprio 1
	s_barrier
	v_mfma_f32_16x16x32_bf16 v[126:129], v[130:133], v[184:187], v[126:129]
	v_mfma_f32_16x16x32_bf16 v[122:125], v[160:163], v[184:187], v[122:125]
	v_mfma_f32_16x16x32_bf16 v[114:117], v[130:133], v[192:195], v[114:117]
	v_mfma_f32_16x16x32_bf16 v[106:109], v[160:163], v[192:195], v[106:109]
	v_mfma_f32_16x16x32_bf16 v[94:97], v[130:133], v[200:203], v[94:97]
	v_mfma_f32_16x16x32_bf16 v[90:93], v[160:163], v[200:203], v[90:93]
	v_mfma_f32_16x16x32_bf16 v[82:85], v[130:133], v[208:211], v[82:85]
	v_mfma_f32_16x16x32_bf16 v[74:77], v[160:163], v[208:211], v[74:77]
	v_mfma_f32_16x16x32_bf16 v[126:129], v[152:155], v[188:191], v[126:129]
	v_mfma_f32_16x16x32_bf16 v[122:125], v[164:167], v[188:191], v[122:125]
	v_mfma_f32_16x16x32_bf16 v[114:117], v[152:155], v[196:199], v[114:117]
	v_mfma_f32_16x16x32_bf16 v[106:109], v[164:167], v[196:199], v[106:109]
	v_mfma_f32_16x16x32_bf16 v[94:97], v[152:155], v[204:207], v[94:97]
	v_mfma_f32_16x16x32_bf16 v[90:93], v[164:167], v[204:207], v[90:93]
	v_mfma_f32_16x16x32_bf16 v[82:85], v[152:155], v[212:215], v[82:85]
	v_mfma_f32_16x16x32_bf16 v[74:77], v[164:167], v[212:215], v[74:77]
	v_mfma_f32_16x16x32_bf16 v[118:121], v[168:171], v[184:187], v[118:121]
	v_mfma_f32_16x16x32_bf16 v[110:113], v[176:179], v[184:187], v[110:113]
	v_mfma_f32_16x16x32_bf16 v[102:105], v[168:171], v[192:195], v[102:105]
	v_mfma_f32_16x16x32_bf16 v[98:101], v[176:179], v[192:195], v[98:101]
	v_mfma_f32_16x16x32_bf16 v[86:89], v[168:171], v[200:203], v[86:89]
	v_mfma_f32_16x16x32_bf16 v[78:81], v[176:179], v[200:203], v[78:81]
	v_mfma_f32_16x16x32_bf16 v[70:73], v[168:171], v[208:211], v[70:73]
	v_mfma_f32_16x16x32_bf16 v[66:69], v[176:179], v[208:211], v[66:69]
	v_mfma_f32_16x16x32_bf16 v[118:121], v[172:175], v[188:191], v[118:121]
	v_mfma_f32_16x16x32_bf16 v[110:113], v[180:183], v[188:191], v[110:113]
	v_mfma_f32_16x16x32_bf16 v[102:105], v[172:175], v[196:199], v[102:105]
	v_mfma_f32_16x16x32_bf16 v[98:101], v[180:183], v[196:199], v[98:101]
	v_mfma_f32_16x16x32_bf16 v[86:89], v[172:175], v[204:207], v[86:89]
	v_mfma_f32_16x16x32_bf16 v[78:81], v[180:183], v[204:207], v[78:81]
	v_mfma_f32_16x16x32_bf16 v[70:73], v[172:175], v[212:215], v[70:73]
	v_mfma_f32_16x16x32_bf16 v[66:69], v[180:183], v[212:215], v[66:69]
	s_setprio 0
	s_barrier
	s_add_i32 s0, s2, s43
	v_lshl_add_u64 v[216:217], v[216:217], 0, s[52:53]
	s_mov_b32 m0, s0
	ds_read_b128 v[184:187], v159 offset:49152
	ds_read_b128 v[188:191], v159 offset:50176
	ds_read_b128 v[192:195], v159 offset:51200
	ds_read_b128 v[196:199], v159 offset:52224
	ds_read_b128 v[200:203], v159 offset:53248
	ds_read_b128 v[204:207], v159 offset:54272
	ds_read_b128 v[208:211], v159 offset:55296
	ds_read_b128 v[212:215], v159 offset:56320
	global_load_lds_dwordx4 v[216:217], off
	s_add_i32 m0, s0, 0x2000
	s_add_u32 s0, s68, 0x40080
	v_lshl_add_u64 v[216:217], v[218:219], 0, s[52:53]
	s_addc_u32 s1, s69, 0
	s_add_i32 s2, s3, s43
	global_load_lds_dwordx4 v[216:217], off
	v_lshl_add_u64 v[216:217], s[0:1], 0, v[136:137]
	s_mov_b32 m0, s2
	s_nop 0
	global_load_lds_dwordx4 v[216:217], off
	v_lshl_add_u64 v[216:217], s[0:1], 0, v[138:139]
	s_add_i32 m0, s2, 0x2000
	s_nop 0
	global_load_lds_dwordx4 v[216:217], off
	v_lshl_add_u64 v[216:217], v[220:221], 0, s[52:53]
	s_mov_b32 m0, s83
	s_nop 0
	global_load_lds_dwordx4 v[216:217], off
	v_lshl_add_u64 v[216:217], v[222:223], 0, s[52:53]
	s_mov_b32 m0, s84
	s_nop 0
	global_load_lds_dwordx4 v[216:217], off
	s_waitcnt vmcnt(8)
	s_waitcnt lgkmcnt(0)
	s_setprio 1
	s_barrier
	v_mfma_f32_16x16x32_bf16 v[62:65], v[130:133], v[184:187], v[62:65]
	v_mfma_f32_16x16x32_bf16 v[58:61], v[160:163], v[184:187], v[58:61]
	v_mfma_f32_16x16x32_bf16 v[46:49], v[130:133], v[192:195], v[46:49]
	v_mfma_f32_16x16x32_bf16 v[42:45], v[160:163], v[192:195], v[42:45]
	v_mfma_f32_16x16x32_bf16 v[30:33], v[130:133], v[200:203], v[30:33]
	v_mfma_f32_16x16x32_bf16 v[26:29], v[160:163], v[200:203], v[26:29]
	v_mfma_f32_16x16x32_bf16 v[14:17], v[130:133], v[208:211], v[14:17]
	v_mfma_f32_16x16x32_bf16 v[10:13], v[160:163], v[208:211], v[10:13]
	v_mfma_f32_16x16x32_bf16 v[62:65], v[152:155], v[188:191], v[62:65]
	v_mfma_f32_16x16x32_bf16 v[58:61], v[164:167], v[188:191], v[58:61]
	v_mfma_f32_16x16x32_bf16 v[46:49], v[152:155], v[196:199], v[46:49]
	v_mfma_f32_16x16x32_bf16 v[42:45], v[164:167], v[196:199], v[42:45]
	v_mfma_f32_16x16x32_bf16 v[30:33], v[152:155], v[204:207], v[30:33]
	v_mfma_f32_16x16x32_bf16 v[26:29], v[164:167], v[204:207], v[26:29]
	v_mfma_f32_16x16x32_bf16 v[14:17], v[152:155], v[212:215], v[14:17]
	v_mfma_f32_16x16x32_bf16 v[10:13], v[164:167], v[212:215], v[10:13]
	v_mfma_f32_16x16x32_bf16 v[54:57], v[168:171], v[184:187], v[54:57]
	v_mfma_f32_16x16x32_bf16 v[50:53], v[176:179], v[184:187], v[50:53]
	v_mfma_f32_16x16x32_bf16 v[38:41], v[168:171], v[192:195], v[38:41]
	v_mfma_f32_16x16x32_bf16 v[34:37], v[176:179], v[192:195], v[34:37]
	v_mfma_f32_16x16x32_bf16 v[22:25], v[168:171], v[200:203], v[22:25]
	v_mfma_f32_16x16x32_bf16 v[18:21], v[176:179], v[200:203], v[18:21]
	v_mfma_f32_16x16x32_bf16 v[6:9], v[168:171], v[208:211], v[6:9]
	v_mfma_f32_16x16x32_bf16 v[2:5], v[176:179], v[208:211], v[2:5]
	v_mfma_f32_16x16x32_bf16 v[54:57], v[172:175], v[188:191], v[54:57]
	v_mfma_f32_16x16x32_bf16 v[50:53], v[180:183], v[188:191], v[50:53]
	v_mfma_f32_16x16x32_bf16 v[38:41], v[172:175], v[196:199], v[38:41]
	v_mfma_f32_16x16x32_bf16 v[34:37], v[180:183], v[196:199], v[34:37]
	v_mfma_f32_16x16x32_bf16 v[22:25], v[172:175], v[204:207], v[22:25]
	v_mfma_f32_16x16x32_bf16 v[18:21], v[180:183], v[204:207], v[18:21]
	v_mfma_f32_16x16x32_bf16 v[6:9], v[172:175], v[212:215], v[6:9]
	v_mfma_f32_16x16x32_bf16 v[2:5], v[180:183], v[212:215], v[2:5]
	s_setprio 0
	s_barrier
	s_add_i32 s91, s91, 2
	s_add_u32 s66, s66, 0x100
	s_addc_u32 s67, s67, 0
	s_add_u32 s89, s89, 0x100
	s_addc_u32 s90, s90, 0
	s_cmp_gt_u32 s91, 13
	s_cbranch_scc0 .LBB0_1797
	s_and_b64 vcc, exec, s[54:55]
	s_cbranch_vccz .LBB0_1800
	s_barrier

.LBB0_2002:
	ds_read_b128 v[158:161], v154
	ds_read_b128 v[162:165], v154 offset:1024
	ds_read_b128 v[166:169], v154 offset:2048
	ds_read_b128 v[170:173], v154 offset:3072
	ds_read_b128 v[174:177], v155
	ds_read_b128 v[178:181], v155 offset:1024
	ds_read_b128 v[182:185], v155 offset:2048
	ds_read_b128 v[186:189], v155 offset:3072
	s_add_u32 s0, s62, 0xfffc0080
	s_addc_u32 s1, s63, -1
	s_cmp_eq_u32 s83, 12
	s_cselect_b32 s67, s55, s1
	s_cselect_b32 s66, s79, s0
	s_cselect_b32 s65, s53, s82
	s_cselect_b32 s64, s80, s81
	v_lshl_add_u64 v[150:151], s[62:63], 0, v[140:141]
	s_add_i32 m0, s61, 0xc000
	ds_read_b128 v[190:193], v156
	ds_read_b128 v[194:197], v156 offset:1024
	ds_read_b128 v[198:201], v156 offset:2048
	ds_read_b128 v[202:205], v156 offset:3072
	ds_read_b128 v[206:209], v156 offset:4096
	ds_read_b128 v[210:213], v156 offset:5120
	ds_read_b128 v[214:217], v156 offset:6144
	ds_read_b128 v[218:221], v156 offset:7168
	global_load_lds_dwordx4 v[150:151], off
	v_lshl_add_u64 v[150:151], s[62:63], 0, v[142:143]
	s_add_i32 m0, s61, 0xe000
	s_nop 0
	global_load_lds_dwordx4 v[150:151], off
	s_waitcnt vmcnt(8)
	s_waitcnt lgkmcnt(0)
	s_setprio 1
	s_barrier
	v_mfma_f32_16x16x32_bf16 v[126:129], v[158:161], v[190:193], v[126:129]
	v_mfma_f32_16x16x32_bf16 v[122:125], v[166:169], v[190:193], v[122:125]
	v_mfma_f32_16x16x32_bf16 v[110:113], v[158:161], v[198:201], v[110:113]
	v_mfma_f32_16x16x32_bf16 v[106:109], v[166:169], v[198:201], v[106:109]
	v_mfma_f32_16x16x32_bf16 v[94:97], v[158:161], v[206:209], v[94:97]
	v_mfma_f32_16x16x32_bf16 v[90:93], v[166:169], v[206:209], v[90:93]
	v_mfma_f32_16x16x32_bf16 v[78:81], v[158:161], v[214:217], v[78:81]
	v_mfma_f32_16x16x32_bf16 v[74:77], v[166:169], v[214:217], v[74:77]
	v_mfma_f32_16x16x32_bf16 v[126:129], v[162:165], v[194:197], v[126:129]
	v_mfma_f32_16x16x32_bf16 v[122:125], v[170:173], v[194:197], v[122:125]
	v_mfma_f32_16x16x32_bf16 v[110:113], v[162:165], v[202:205], v[110:113]
	v_mfma_f32_16x16x32_bf16 v[106:109], v[170:173], v[202:205], v[106:109]
	v_mfma_f32_16x16x32_bf16 v[94:97], v[162:165], v[210:213], v[94:97]
	v_mfma_f32_16x16x32_bf16 v[90:93], v[170:173], v[210:213], v[90:93]
	v_mfma_f32_16x16x32_bf16 v[78:81], v[162:165], v[218:221], v[78:81]
	v_mfma_f32_16x16x32_bf16 v[74:77], v[170:173], v[218:221], v[74:77]
	v_mfma_f32_16x16x32_bf16 v[118:121], v[174:177], v[190:193], v[118:121]
	v_mfma_f32_16x16x32_bf16 v[114:117], v[182:185], v[190:193], v[114:117]
	v_mfma_f32_16x16x32_bf16 v[102:105], v[174:177], v[198:201], v[102:105]
	v_mfma_f32_16x16x32_bf16 v[98:101], v[182:185], v[198:201], v[98:101]
	v_mfma_f32_16x16x32_bf16 v[86:89], v[174:177], v[206:209], v[86:89]
	v_mfma_f32_16x16x32_bf16 v[82:85], v[182:185], v[206:209], v[82:85]
	v_mfma_f32_16x16x32_bf16 v[70:73], v[174:177], v[214:217], v[70:73]
	v_mfma_f32_16x16x32_bf16 v[66:69], v[182:185], v[214:217], v[66:69]
	v_mfma_f32_16x16x32_bf16 v[118:121], v[178:181], v[194:197], v[118:121]
	v_mfma_f32_16x16x32_bf16 v[114:117], v[186:189], v[194:197], v[114:117]
	v_mfma_f32_16x16x32_bf16 v[102:105], v[178:181], v[202:205], v[102:105]
	v_mfma_f32_16x16x32_bf16 v[98:101], v[186:189], v[202:205], v[98:101]
	v_mfma_f32_16x16x32_bf16 v[86:89], v[178:181], v[210:213], v[86:89]
	v_mfma_f32_16x16x32_bf16 v[82:85], v[186:189], v[210:213], v[82:85]
	v_mfma_f32_16x16x32_bf16 v[70:73], v[178:181], v[218:221], v[70:73]
	v_mfma_f32_16x16x32_bf16 v[66:69], v[186:189], v[218:221], v[66:69]
	s_setprio 0
	s_barrier
	s_add_i32 s0, s76, s68
	v_lshl_add_u64 v[150:151], s[64:65], 0, v[134:135]
	s_mov_b32 m0, s0
	ds_read_b128 v[190:193], v156 offset:16384
	ds_read_b128 v[194:197], v156 offset:17408
	ds_read_b128 v[198:201], v156 offset:18432
	ds_read_b128 v[202:205], v156 offset:19456
	ds_read_b128 v[206:209], v156 offset:20480
	ds_read_b128 v[210:213], v156 offset:21504
	ds_read_b128 v[214:217], v156 offset:22528
	ds_read_b128 v[218:221], v156 offset:23552
	global_load_lds_dwordx4 v[150:151], off
	s_add_i32 m0, s0, 0x2000
	s_add_u32 s0, s64, 0x40000
	v_lshl_add_u64 v[222:223], s[64:65], 0, v[138:139]
	s_addc_u32 s1, s65, 0
	s_add_i32 s6, s77, s68
	global_load_lds_dwordx4 v[222:223], off
	v_lshl_add_u64 v[224:225], s[0:1], 0, v[134:135]
	s_mov_b32 m0, s6
	v_lshl_add_u64 v[226:227], s[66:67], 0, v[136:137]
	global_load_lds_dwordx4 v[224:225], off
	v_lshl_add_u64 v[224:225], s[0:1], 0, v[138:139]
	s_add_i32 m0, s6, 0x2000
	s_nop 0
	global_load_lds_dwordx4 v[224:225], off
	v_lshl_add_u64 v[224:225], s[66:67], 0, v[132:133]
	s_mov_b32 m0, s61
	s_nop 0
	global_load_lds_dwordx4 v[224:225], off
	s_mov_b32 m0, s70
	s_nop 0
	global_load_lds_dwordx4 v[226:227], off
	s_waitcnt vmcnt(8)
	s_waitcnt lgkmcnt(0)
	s_setprio 1
	s_barrier
	v_mfma_f32_16x16x32_bf16 v[62:65], v[158:161], v[190:193], v[62:65]
	v_mfma_f32_16x16x32_bf16 v[58:61], v[166:169], v[190:193], v[58:61]
	v_mfma_f32_16x16x32_bf16 v[46:49], v[158:161], v[198:201], v[46:49]
	v_mfma_f32_16x16x32_bf16 v[42:45], v[166:169], v[198:201], v[42:45]
	v_mfma_f32_16x16x32_bf16 v[30:33], v[158:161], v[206:209], v[30:33]
	v_mfma_f32_16x16x32_bf16 v[26:29], v[166:169], v[206:209], v[26:29]
	v_mfma_f32_16x16x32_bf16 v[14:17], v[158:161], v[214:217], v[14:17]
	v_mfma_f32_16x16x32_bf16 v[10:13], v[166:169], v[214:217], v[10:13]
	v_mfma_f32_16x16x32_bf16 v[62:65], v[162:165], v[194:197], v[62:65]
	v_mfma_f32_16x16x32_bf16 v[58:61], v[170:173], v[194:197], v[58:61]
	v_mfma_f32_16x16x32_bf16 v[46:49], v[162:165], v[202:205], v[46:49]
	v_mfma_f32_16x16x32_bf16 v[42:45], v[170:173], v[202:205], v[42:45]
	v_mfma_f32_16x16x32_bf16 v[30:33], v[162:165], v[210:213], v[30:33]
	v_mfma_f32_16x16x32_bf16 v[26:29], v[170:173], v[210:213], v[26:29]
	v_mfma_f32_16x16x32_bf16 v[14:17], v[162:165], v[218:221], v[14:17]
	v_mfma_f32_16x16x32_bf16 v[10:13], v[170:173], v[218:221], v[10:13]
	v_mfma_f32_16x16x32_bf16 v[54:57], v[174:177], v[190:193], v[54:57]
	v_mfma_f32_16x16x32_bf16 v[50:53], v[182:185], v[190:193], v[50:53]
	v_mfma_f32_16x16x32_bf16 v[38:41], v[174:177], v[198:201], v[38:41]
	v_mfma_f32_16x16x32_bf16 v[34:37], v[182:185], v[198:201], v[34:37]
	v_mfma_f32_16x16x32_bf16 v[22:25], v[174:177], v[206:209], v[22:25]
	v_mfma_f32_16x16x32_bf16 v[18:21], v[182:185], v[206:209], v[18:21]
	v_mfma_f32_16x16x32_bf16 v[6:9], v[174:177], v[214:217], v[6:9]
	v_mfma_f32_16x16x32_bf16 v[2:5], v[182:185], v[214:217], v[2:5]
	v_mfma_f32_16x16x32_bf16 v[54:57], v[178:181], v[194:197], v[54:57]
	v_mfma_f32_16x16x32_bf16 v[50:53], v[186:189], v[194:197], v[50:53]
	v_mfma_f32_16x16x32_bf16 v[38:41], v[178:181], v[202:205], v[38:41]
	v_mfma_f32_16x16x32_bf16 v[34:37], v[186:189], v[202:205], v[34:37]
	v_mfma_f32_16x16x32_bf16 v[22:25], v[178:181], v[210:213], v[22:25]
	v_mfma_f32_16x16x32_bf16 v[18:21], v[186:189], v[210:213], v[18:21]
	v_mfma_f32_16x16x32_bf16 v[6:9], v[178:181], v[218:221], v[6:9]
	v_mfma_f32_16x16x32_bf16 v[2:5], v[186:189], v[218:221], v[2:5]
	s_setprio 0
	s_barrier
	s_add_i32 s6, 0, 0x18000
	v_add_u32_e32 v157, s6, v152
	s_add_i32 s7, 0, 0x1c000
	ds_read_b128 v[158:161], v157
	ds_read_b128 v[162:165], v157 offset:1024
	ds_read_b128 v[166:169], v157 offset:2048
	ds_read_b128 v[170:173], v157 offset:3072
	v_add_u32_e32 v157, s7, v152
	ds_read_b128 v[174:177], v157
	ds_read_b128 v[178:181], v157 offset:1024
	ds_read_b128 v[182:185], v157 offset:2048
	ds_read_b128 v[186:189], v157 offset:3072
	s_add_u32 s0, s66, 0x40000
	s_addc_u32 s1, s67, 0
	s_mov_b32 m0, s71
	v_lshl_add_u64 v[228:229], s[0:1], 0, v[132:133]
	ds_read_b128 v[190:193], v156 offset:32768
	ds_read_b128 v[194:197], v156 offset:33792
	ds_read_b128 v[198:201], v156 offset:34816
	ds_read_b128 v[202:205], v156 offset:35840
	ds_read_b128 v[206:209], v156 offset:36864
	ds_read_b128 v[210:213], v156 offset:37888
	ds_read_b128 v[214:217], v156 offset:38912
	ds_read_b128 v[218:221], v156 offset:39936
	global_load_lds_dwordx4 v[228:229], off
	v_lshl_add_u64 v[228:229], s[0:1], 0, v[136:137]
	s_mov_b32 m0, s72
	s_nop 0
	global_load_lds_dwordx4 v[228:229], off
	s_waitcnt vmcnt(8)
	s_waitcnt lgkmcnt(0)
	s_setprio 1
	s_barrier
	v_mfma_f32_16x16x32_bf16 v[126:129], v[158:161], v[190:193], v[126:129]
	v_mfma_f32_16x16x32_bf16 v[122:125], v[166:169], v[190:193], v[122:125]
	v_mfma_f32_16x16x32_bf16 v[110:113], v[158:161], v[198:201], v[110:113]
	v_mfma_f32_16x16x32_bf16 v[106:109], v[166:169], v[198:201], v[106:109]
	v_mfma_f32_16x16x32_bf16 v[94:97], v[158:161], v[206:209], v[94:97]
	v_mfma_f32_16x16x32_bf16 v[90:93], v[166:169], v[206:209], v[90:93]
	v_mfma_f32_16x16x32_bf16 v[78:81], v[158:161], v[214:217], v[78:81]
	v_mfma_f32_16x16x32_bf16 v[74:77], v[166:169], v[214:217], v[74:77]
	v_mfma_f32_16x16x32_bf16 v[126:129], v[162:165], v[194:197], v[126:129]
	v_mfma_f32_16x16x32_bf16 v[122:125], v[170:173], v[194:197], v[122:125]
	v_mfma_f32_16x16x32_bf16 v[110:113], v[162:165], v[202:205], v[110:113]
	v_mfma_f32_16x16x32_bf16 v[106:109], v[170:173], v[202:205], v[106:109]
	v_mfma_f32_16x16x32_bf16 v[94:97], v[162:165], v[210:213], v[94:97]
	v_mfma_f32_16x16x32_bf16 v[90:93], v[170:173], v[210:213], v[90:93]
	v_mfma_f32_16x16x32_bf16 v[78:81], v[162:165], v[218:221], v[78:81]
	v_mfma_f32_16x16x32_bf16 v[74:77], v[170:173], v[218:221], v[74:77]
	v_mfma_f32_16x16x32_bf16 v[118:121], v[174:177], v[190:193], v[118:121]
	v_mfma_f32_16x16x32_bf16 v[114:117], v[182:185], v[190:193], v[114:117]
	v_mfma_f32_16x16x32_bf16 v[102:105], v[174:177], v[198:201], v[102:105]
	v_mfma_f32_16x16x32_bf16 v[98:101], v[182:185], v[198:201], v[98:101]
	v_mfma_f32_16x16x32_bf16 v[86:89], v[174:177], v[206:209], v[86:89]
	v_mfma_f32_16x16x32_bf16 v[82:85], v[182:185], v[206:209], v[82:85]
	v_mfma_f32_16x16x32_bf16 v[70:73], v[174:177], v[214:217], v[70:73]
	v_mfma_f32_16x16x32_bf16 v[66:69], v[182:185], v[214:217], v[66:69]
	v_mfma_f32_16x16x32_bf16 v[118:121], v[178:181], v[194:197], v[118:121]
	v_mfma_f32_16x16x32_bf16 v[114:117], v[186:189], v[194:197], v[114:117]
	v_mfma_f32_16x16x32_bf16 v[102:105], v[178:181], v[202:205], v[102:105]
	v_mfma_f32_16x16x32_bf16 v[98:101], v[186:189], v[202:205], v[98:101]
	v_mfma_f32_16x16x32_bf16 v[86:89], v[178:181], v[210:213], v[86:89]
	v_mfma_f32_16x16x32_bf16 v[82:85], v[186:189], v[210:213], v[82:85]
	v_mfma_f32_16x16x32_bf16 v[70:73], v[178:181], v[218:221], v[70:73]
	v_mfma_f32_16x16x32_bf16 v[66:69], v[186:189], v[218:221], v[66:69]
	s_setprio 0
	s_barrier
	s_add_i32 s0, s6, s68
	v_lshl_add_u64 v[150:151], v[150:151], 0, s[48:49]
	s_mov_b32 m0, s0
	ds_read_b128 v[190:193], v156 offset:49152
	ds_read_b128 v[194:197], v156 offset:50176
	ds_read_b128 v[198:201], v156 offset:51200
	ds_read_b128 v[202:205], v156 offset:52224
	ds_read_b128 v[206:209], v156 offset:53248
	ds_read_b128 v[210:213], v156 offset:54272
	ds_read_b128 v[214:217], v156 offset:55296
	ds_read_b128 v[218:221], v156 offset:56320
	global_load_lds_dwordx4 v[150:151], off
	s_add_i32 m0, s0, 0x2000
	s_add_u32 s0, s64, 0x40080
	v_lshl_add_u64 v[150:151], v[222:223], 0, s[48:49]
	s_addc_u32 s1, s65, 0
	s_add_i32 s6, s7, s68
	global_load_lds_dwordx4 v[150:151], off
	v_lshl_add_u64 v[150:151], s[0:1], 0, v[134:135]
	s_mov_b32 m0, s6
	s_nop 0
	global_load_lds_dwordx4 v[150:151], off
	v_lshl_add_u64 v[150:151], s[0:1], 0, v[138:139]
	s_add_i32 m0, s6, 0x2000
	s_nop 0
	global_load_lds_dwordx4 v[150:151], off
	v_lshl_add_u64 v[150:151], v[224:225], 0, s[48:49]
	s_mov_b32 m0, s74
	s_nop 0
	global_load_lds_dwordx4 v[150:151], off
	v_lshl_add_u64 v[150:151], v[226:227], 0, s[48:49]
	s_mov_b32 m0, s75
	s_nop 0
	global_load_lds_dwordx4 v[150:151], off
	s_waitcnt vmcnt(8)
	s_waitcnt lgkmcnt(0)
	s_setprio 1
	s_barrier
	v_mfma_f32_16x16x32_bf16 v[62:65], v[158:161], v[190:193], v[62:65]
	v_mfma_f32_16x16x32_bf16 v[58:61], v[166:169], v[190:193], v[58:61]
	v_mfma_f32_16x16x32_bf16 v[46:49], v[158:161], v[198:201], v[46:49]
	v_mfma_f32_16x16x32_bf16 v[42:45], v[166:169], v[198:201], v[42:45]
	v_mfma_f32_16x16x32_bf16 v[30:33], v[158:161], v[206:209], v[30:33]
	v_mfma_f32_16x16x32_bf16 v[26:29], v[166:169], v[206:209], v[26:29]
	v_mfma_f32_16x16x32_bf16 v[14:17], v[158:161], v[214:217], v[14:17]
	v_mfma_f32_16x16x32_bf16 v[10:13], v[166:169], v[214:217], v[10:13]
	v_mfma_f32_16x16x32_bf16 v[62:65], v[162:165], v[194:197], v[62:65]
	v_mfma_f32_16x16x32_bf16 v[58:61], v[170:173], v[194:197], v[58:61]
	v_mfma_f32_16x16x32_bf16 v[46:49], v[162:165], v[202:205], v[46:49]
	v_mfma_f32_16x16x32_bf16 v[42:45], v[170:173], v[202:205], v[42:45]
	v_mfma_f32_16x16x32_bf16 v[30:33], v[162:165], v[210:213], v[30:33]
	v_mfma_f32_16x16x32_bf16 v[26:29], v[170:173], v[210:213], v[26:29]
	v_mfma_f32_16x16x32_bf16 v[14:17], v[162:165], v[218:221], v[14:17]
	v_mfma_f32_16x16x32_bf16 v[10:13], v[170:173], v[218:221], v[10:13]
	v_mfma_f32_16x16x32_bf16 v[54:57], v[174:177], v[190:193], v[54:57]
	v_mfma_f32_16x16x32_bf16 v[50:53], v[182:185], v[190:193], v[50:53]
	v_mfma_f32_16x16x32_bf16 v[38:41], v[174:177], v[198:201], v[38:41]
	v_mfma_f32_16x16x32_bf16 v[34:37], v[182:185], v[198:201], v[34:37]
	v_mfma_f32_16x16x32_bf16 v[22:25], v[174:177], v[206:209], v[22:25]
	v_mfma_f32_16x16x32_bf16 v[18:21], v[182:185], v[206:209], v[18:21]
	v_mfma_f32_16x16x32_bf16 v[6:9], v[174:177], v[214:217], v[6:9]
	v_mfma_f32_16x16x32_bf16 v[2:5], v[182:185], v[214:217], v[2:5]
	v_mfma_f32_16x16x32_bf16 v[54:57], v[178:181], v[194:197], v[54:57]
	v_mfma_f32_16x16x32_bf16 v[50:53], v[186:189], v[194:197], v[50:53]
	v_mfma_f32_16x16x32_bf16 v[38:41], v[178:181], v[202:205], v[38:41]
	v_mfma_f32_16x16x32_bf16 v[34:37], v[186:189], v[202:205], v[34:37]
	v_mfma_f32_16x16x32_bf16 v[22:25], v[178:181], v[210:213], v[22:25]
	v_mfma_f32_16x16x32_bf16 v[18:21], v[186:189], v[210:213], v[18:21]
	v_mfma_f32_16x16x32_bf16 v[6:9], v[178:181], v[218:221], v[6:9]
	v_mfma_f32_16x16x32_bf16 v[2:5], v[186:189], v[218:221], v[2:5]
	s_setprio 0
	s_barrier
	s_add_i32 s83, s83, 2
	s_add_u32 s62, s62, 0x100
	s_addc_u32 s63, s63, 0
	s_add_u32 s81, s81, 0x100
	s_addc_u32 s82, s82, 0
	s_cmp_gt_u32 s83, 13
	s_cbranch_scc0 .LBB0_2002
	s_and_b64 vcc, exec, s[50:51]
	s_cbranch_vccz .LBB0_2005
	s_barrier

.LBB0_2141:
	ds_read_b128 v[142:145], v151
	ds_read_b128 v[154:157], v151 offset:1024
	ds_read_b128 v[158:161], v151 offset:2048
	ds_read_b128 v[162:165], v151 offset:3072
	ds_read_b128 v[166:169], v152
	ds_read_b128 v[170:173], v152 offset:1024
	ds_read_b128 v[174:177], v152 offset:2048
	ds_read_b128 v[178:181], v152 offset:3072
	s_add_u32 s0, s6, 0xfff00080
	s_addc_u32 s1, s7, -1
	s_cmp_eq_u32 s59, 60
	s_cselect_b32 s29, s21, s1
	s_cselect_b32 s28, s55, s0
	s_cselect_b32 s27, s19, s58
	s_cselect_b32 s26, s56, s57
	v_lshl_add_u64 v[214:215], s[6:7], 0, v[134:135]
	s_add_i32 m0, s34, 0xc000
	ds_read_b128 v[182:185], v153
	ds_read_b128 v[186:189], v153 offset:1024
	ds_read_b128 v[190:193], v153 offset:2048
	ds_read_b128 v[194:197], v153 offset:3072
	ds_read_b128 v[198:201], v153 offset:4096
	ds_read_b128 v[202:205], v153 offset:5120
	ds_read_b128 v[206:209], v153 offset:6144
	ds_read_b128 v[210:213], v153 offset:7168
	global_load_lds_dwordx4 v[214:215], off
	v_lshl_add_u64 v[214:215], s[6:7], 0, v[136:137]
	s_add_i32 m0, s34, 0xe000
	s_nop 0
	global_load_lds_dwordx4 v[214:215], off
	s_waitcnt vmcnt(8)
	s_waitcnt lgkmcnt(0)
	s_setprio 1
	s_barrier
	v_mfma_f32_16x16x32_bf16 v[124:127], v[142:145], v[182:185], v[124:127]
	v_mfma_f32_16x16x32_bf16 v[120:123], v[158:161], v[182:185], v[120:123]
	v_mfma_f32_16x16x32_bf16 v[112:115], v[142:145], v[190:193], v[112:115]
	v_mfma_f32_16x16x32_bf16 v[104:107], v[158:161], v[190:193], v[104:107]
	v_mfma_f32_16x16x32_bf16 v[92:95], v[142:145], v[198:201], v[92:95]
	v_mfma_f32_16x16x32_bf16 v[88:91], v[158:161], v[198:201], v[88:91]
	v_mfma_f32_16x16x32_bf16 v[80:83], v[142:145], v[206:209], v[80:83]
	v_mfma_f32_16x16x32_bf16 v[72:75], v[158:161], v[206:209], v[72:75]
	v_mfma_f32_16x16x32_bf16 v[124:127], v[154:157], v[186:189], v[124:127]
	v_mfma_f32_16x16x32_bf16 v[120:123], v[162:165], v[186:189], v[120:123]
	v_mfma_f32_16x16x32_bf16 v[112:115], v[154:157], v[194:197], v[112:115]
	v_mfma_f32_16x16x32_bf16 v[104:107], v[162:165], v[194:197], v[104:107]
	v_mfma_f32_16x16x32_bf16 v[92:95], v[154:157], v[202:205], v[92:95]
	v_mfma_f32_16x16x32_bf16 v[88:91], v[162:165], v[202:205], v[88:91]
	v_mfma_f32_16x16x32_bf16 v[80:83], v[154:157], v[210:213], v[80:83]
	v_mfma_f32_16x16x32_bf16 v[72:75], v[162:165], v[210:213], v[72:75]
	v_mfma_f32_16x16x32_bf16 v[116:119], v[166:169], v[182:185], v[116:119]
	v_mfma_f32_16x16x32_bf16 v[108:111], v[174:177], v[182:185], v[108:111]
	v_mfma_f32_16x16x32_bf16 v[100:103], v[166:169], v[190:193], v[100:103]
	v_mfma_f32_16x16x32_bf16 v[96:99], v[174:177], v[190:193], v[96:99]
	v_mfma_f32_16x16x32_bf16 v[84:87], v[166:169], v[198:201], v[84:87]
	v_mfma_f32_16x16x32_bf16 v[76:79], v[174:177], v[198:201], v[76:79]
	v_mfma_f32_16x16x32_bf16 v[68:71], v[166:169], v[206:209], v[68:71]
	v_mfma_f32_16x16x32_bf16 v[64:67], v[174:177], v[206:209], v[64:67]
	v_mfma_f32_16x16x32_bf16 v[116:119], v[170:173], v[186:189], v[116:119]
	v_mfma_f32_16x16x32_bf16 v[108:111], v[178:181], v[186:189], v[108:111]
	v_mfma_f32_16x16x32_bf16 v[100:103], v[170:173], v[194:197], v[100:103]
	v_mfma_f32_16x16x32_bf16 v[96:99], v[178:181], v[194:197], v[96:99]
	v_mfma_f32_16x16x32_bf16 v[84:87], v[170:173], v[202:205], v[84:87]
	v_mfma_f32_16x16x32_bf16 v[76:79], v[178:181], v[202:205], v[76:79]
	v_mfma_f32_16x16x32_bf16 v[68:71], v[170:173], v[210:213], v[68:71]
	v_mfma_f32_16x16x32_bf16 v[64:67], v[178:181], v[210:213], v[64:67]
	s_setprio 0
	s_barrier
	s_add_i32 s0, s52, s30
	v_lshl_add_u64 v[214:215], s[26:27], 0, v[130:131]
	s_mov_b32 m0, s0
	ds_read_b128 v[182:185], v153 offset:16384
	ds_read_b128 v[186:189], v153 offset:17408
	ds_read_b128 v[190:193], v153 offset:18432
	ds_read_b128 v[194:197], v153 offset:19456
	ds_read_b128 v[198:201], v153 offset:20480
	ds_read_b128 v[202:205], v153 offset:21504
	ds_read_b128 v[206:209], v153 offset:22528
	ds_read_b128 v[210:213], v153 offset:23552
	global_load_lds_dwordx4 v[214:215], off
	s_add_i32 m0, s0, 0x2000
	s_add_u32 s0, s26, 0x100000
	v_lshl_add_u64 v[216:217], s[26:27], 0, v[132:133]
	s_addc_u32 s1, s27, 0
	s_add_i32 s60, s53, s30
	global_load_lds_dwordx4 v[216:217], off
	v_lshl_add_u64 v[218:219], s[0:1], 0, v[130:131]
	s_mov_b32 m0, s60
	v_lshl_add_u64 v[220:221], s[28:29], 0, v[132:133]
	global_load_lds_dwordx4 v[218:219], off
	v_lshl_add_u64 v[218:219], s[0:1], 0, v[132:133]
	s_add_i32 m0, s60, 0x2000
	s_nop 0
	global_load_lds_dwordx4 v[218:219], off
	v_lshl_add_u64 v[218:219], s[28:29], 0, v[130:131]
	s_mov_b32 m0, s34
	s_nop 0
	global_load_lds_dwordx4 v[218:219], off
	s_mov_b32 m0, s35
	s_nop 0
	global_load_lds_dwordx4 v[220:221], off
	s_waitcnt vmcnt(8)
	s_waitcnt lgkmcnt(0)
	s_setprio 1
	s_barrier
	v_mfma_f32_16x16x32_bf16 v[60:63], v[142:145], v[182:185], v[60:63]
	v_mfma_f32_16x16x32_bf16 v[56:59], v[158:161], v[182:185], v[56:59]
	v_mfma_f32_16x16x32_bf16 v[48:51], v[142:145], v[190:193], v[48:51]
	v_mfma_f32_16x16x32_bf16 v[40:43], v[158:161], v[190:193], v[40:43]
	v_mfma_f32_16x16x32_bf16 v[28:31], v[142:145], v[198:201], v[28:31]
	v_mfma_f32_16x16x32_bf16 v[24:27], v[158:161], v[198:201], v[24:27]
	v_mfma_f32_16x16x32_bf16 v[16:19], v[142:145], v[206:209], v[16:19]
	v_mfma_f32_16x16x32_bf16 v[8:11], v[158:161], v[206:209], v[8:11]
	v_mfma_f32_16x16x32_bf16 v[60:63], v[154:157], v[186:189], v[60:63]
	v_mfma_f32_16x16x32_bf16 v[56:59], v[162:165], v[186:189], v[56:59]
	v_mfma_f32_16x16x32_bf16 v[48:51], v[154:157], v[194:197], v[48:51]
	v_mfma_f32_16x16x32_bf16 v[40:43], v[162:165], v[194:197], v[40:43]
	v_mfma_f32_16x16x32_bf16 v[28:31], v[154:157], v[202:205], v[28:31]
	v_mfma_f32_16x16x32_bf16 v[24:27], v[162:165], v[202:205], v[24:27]
	v_mfma_f32_16x16x32_bf16 v[16:19], v[154:157], v[210:213], v[16:19]
	v_mfma_f32_16x16x32_bf16 v[8:11], v[162:165], v[210:213], v[8:11]
	v_mfma_f32_16x16x32_bf16 v[52:55], v[166:169], v[182:185], v[52:55]
	v_mfma_f32_16x16x32_bf16 v[44:47], v[174:177], v[182:185], v[44:47]
	v_mfma_f32_16x16x32_bf16 v[36:39], v[166:169], v[190:193], v[36:39]
	v_mfma_f32_16x16x32_bf16 v[32:35], v[174:177], v[190:193], v[32:35]
	v_mfma_f32_16x16x32_bf16 v[20:23], v[166:169], v[198:201], v[20:23]
	v_mfma_f32_16x16x32_bf16 v[12:15], v[174:177], v[198:201], v[12:15]
	v_mfma_f32_16x16x32_bf16 v[4:7], v[166:169], v[206:209], v[4:7]
	v_mfma_f32_16x16x32_bf16 v[0:3], v[174:177], v[206:209], v[0:3]
	v_mfma_f32_16x16x32_bf16 v[52:55], v[170:173], v[186:189], v[52:55]
	v_mfma_f32_16x16x32_bf16 v[44:47], v[178:181], v[186:189], v[44:47]
	v_mfma_f32_16x16x32_bf16 v[36:39], v[170:173], v[194:197], v[36:39]
	v_mfma_f32_16x16x32_bf16 v[32:35], v[178:181], v[194:197], v[32:35]
	v_mfma_f32_16x16x32_bf16 v[20:23], v[170:173], v[202:205], v[20:23]
	v_mfma_f32_16x16x32_bf16 v[12:15], v[178:181], v[202:205], v[12:15]
	v_mfma_f32_16x16x32_bf16 v[4:7], v[170:173], v[210:213], v[4:7]
	v_mfma_f32_16x16x32_bf16 v[0:3], v[178:181], v[210:213], v[0:3]
	s_setprio 0
	s_barrier
	s_add_i32 s60, 0, 0x18000
	s_add_i32 s61, 0, 0x1c000
	v_add_u32_e32 v162, s60, v147
	v_add_u32_e32 v178, s61, v147
	ds_read_b128 v[142:145], v162
	ds_read_b128 v[154:157], v162 offset:1024
	ds_read_b128 v[158:161], v162 offset:2048
	ds_read_b128 v[162:165], v162 offset:3072
	ds_read_b128 v[166:169], v178
	ds_read_b128 v[170:173], v178 offset:1024
	ds_read_b128 v[174:177], v178 offset:2048
	ds_read_b128 v[178:181], v178 offset:3072
	s_add_u32 s0, s28, 0x100000
	s_addc_u32 s1, s29, 0
	s_mov_b32 m0, s36
	v_lshl_add_u64 v[222:223], s[0:1], 0, v[130:131]
	ds_read_b128 v[182:185], v153 offset:32768
	ds_read_b128 v[186:189], v153 offset:33792
	ds_read_b128 v[190:193], v153 offset:34816
	ds_read_b128 v[194:197], v153 offset:35840
	ds_read_b128 v[198:201], v153 offset:36864
	ds_read_b128 v[202:205], v153 offset:37888
	ds_read_b128 v[206:209], v153 offset:38912
	ds_read_b128 v[210:213], v153 offset:39936
	global_load_lds_dwordx4 v[222:223], off
	v_lshl_add_u64 v[222:223], s[0:1], 0, v[132:133]
	s_mov_b32 m0, s37
	s_nop 0
	global_load_lds_dwordx4 v[222:223], off
	s_waitcnt vmcnt(8)
	s_waitcnt lgkmcnt(0)
	s_setprio 1
	s_barrier
	v_mfma_f32_16x16x32_bf16 v[124:127], v[142:145], v[182:185], v[124:127]
	v_mfma_f32_16x16x32_bf16 v[120:123], v[158:161], v[182:185], v[120:123]
	v_mfma_f32_16x16x32_bf16 v[112:115], v[142:145], v[190:193], v[112:115]
	v_mfma_f32_16x16x32_bf16 v[104:107], v[158:161], v[190:193], v[104:107]
	v_mfma_f32_16x16x32_bf16 v[92:95], v[142:145], v[198:201], v[92:95]
	v_mfma_f32_16x16x32_bf16 v[88:91], v[158:161], v[198:201], v[88:91]
	v_mfma_f32_16x16x32_bf16 v[80:83], v[142:145], v[206:209], v[80:83]
	v_mfma_f32_16x16x32_bf16 v[72:75], v[158:161], v[206:209], v[72:75]
	v_mfma_f32_16x16x32_bf16 v[124:127], v[154:157], v[186:189], v[124:127]
	v_mfma_f32_16x16x32_bf16 v[120:123], v[162:165], v[186:189], v[120:123]
	v_mfma_f32_16x16x32_bf16 v[112:115], v[154:157], v[194:197], v[112:115]
	v_mfma_f32_16x16x32_bf16 v[104:107], v[162:165], v[194:197], v[104:107]
	v_mfma_f32_16x16x32_bf16 v[92:95], v[154:157], v[202:205], v[92:95]
	v_mfma_f32_16x16x32_bf16 v[88:91], v[162:165], v[202:205], v[88:91]
	v_mfma_f32_16x16x32_bf16 v[80:83], v[154:157], v[210:213], v[80:83]
	v_mfma_f32_16x16x32_bf16 v[72:75], v[162:165], v[210:213], v[72:75]
	v_mfma_f32_16x16x32_bf16 v[116:119], v[166:169], v[182:185], v[116:119]
	v_mfma_f32_16x16x32_bf16 v[108:111], v[174:177], v[182:185], v[108:111]
	v_mfma_f32_16x16x32_bf16 v[100:103], v[166:169], v[190:193], v[100:103]
	v_mfma_f32_16x16x32_bf16 v[96:99], v[174:177], v[190:193], v[96:99]
	v_mfma_f32_16x16x32_bf16 v[84:87], v[166:169], v[198:201], v[84:87]
	v_mfma_f32_16x16x32_bf16 v[76:79], v[174:177], v[198:201], v[76:79]
	v_mfma_f32_16x16x32_bf16 v[68:71], v[166:169], v[206:209], v[68:71]
	v_mfma_f32_16x16x32_bf16 v[64:67], v[174:177], v[206:209], v[64:67]
	v_mfma_f32_16x16x32_bf16 v[116:119], v[170:173], v[186:189], v[116:119]
	v_mfma_f32_16x16x32_bf16 v[108:111], v[178:181], v[186:189], v[108:111]
	v_mfma_f32_16x16x32_bf16 v[100:103], v[170:173], v[194:197], v[100:103]
	v_mfma_f32_16x16x32_bf16 v[96:99], v[178:181], v[194:197], v[96:99]
	v_mfma_f32_16x16x32_bf16 v[84:87], v[170:173], v[202:205], v[84:87]
	v_mfma_f32_16x16x32_bf16 v[76:79], v[178:181], v[202:205], v[76:79]
	v_mfma_f32_16x16x32_bf16 v[68:71], v[170:173], v[210:213], v[68:71]
	v_mfma_f32_16x16x32_bf16 v[64:67], v[178:181], v[210:213], v[64:67]
	s_setprio 0
	s_barrier
	s_add_i32 s0, s60, s30
	v_lshl_add_u64 v[214:215], v[214:215], 0, s[14:15]
	s_mov_b32 m0, s0
	ds_read_b128 v[182:185], v153 offset:49152
	ds_read_b128 v[186:189], v153 offset:50176
	ds_read_b128 v[190:193], v153 offset:51200
	ds_read_b128 v[194:197], v153 offset:52224
	ds_read_b128 v[198:201], v153 offset:53248
	ds_read_b128 v[202:205], v153 offset:54272
	ds_read_b128 v[206:209], v153 offset:55296
	ds_read_b128 v[210:213], v153 offset:56320
	global_load_lds_dwordx4 v[214:215], off
	s_add_i32 m0, s0, 0x2000
	s_add_u32 s0, s26, 0x100080
	v_lshl_add_u64 v[214:215], v[216:217], 0, s[14:15]
	s_addc_u32 s1, s27, 0
	s_add_i32 s26, s61, s30
	global_load_lds_dwordx4 v[214:215], off
	v_lshl_add_u64 v[214:215], s[0:1], 0, v[130:131]
	s_mov_b32 m0, s26
	s_nop 0
	global_load_lds_dwordx4 v[214:215], off
	v_lshl_add_u64 v[214:215], s[0:1], 0, v[132:133]
	s_add_i32 m0, s26, 0x2000
	s_nop 0
	global_load_lds_dwordx4 v[214:215], off
	v_lshl_add_u64 v[214:215], v[218:219], 0, s[14:15]
	s_mov_b32 m0, s49
	s_nop 0
	global_load_lds_dwordx4 v[214:215], off
	v_lshl_add_u64 v[214:215], v[220:221], 0, s[14:15]
	s_mov_b32 m0, s50
	s_nop 0
	global_load_lds_dwordx4 v[214:215], off
	s_waitcnt vmcnt(8)
	s_waitcnt lgkmcnt(0)
	s_setprio 1
	s_barrier
	v_mfma_f32_16x16x32_bf16 v[60:63], v[142:145], v[182:185], v[60:63]
	v_mfma_f32_16x16x32_bf16 v[56:59], v[158:161], v[182:185], v[56:59]
	v_mfma_f32_16x16x32_bf16 v[48:51], v[142:145], v[190:193], v[48:51]
	v_mfma_f32_16x16x32_bf16 v[40:43], v[158:161], v[190:193], v[40:43]
	v_mfma_f32_16x16x32_bf16 v[28:31], v[142:145], v[198:201], v[28:31]
	v_mfma_f32_16x16x32_bf16 v[24:27], v[158:161], v[198:201], v[24:27]
	v_mfma_f32_16x16x32_bf16 v[16:19], v[142:145], v[206:209], v[16:19]
	v_mfma_f32_16x16x32_bf16 v[8:11], v[158:161], v[206:209], v[8:11]
	v_mfma_f32_16x16x32_bf16 v[60:63], v[154:157], v[186:189], v[60:63]
	v_mfma_f32_16x16x32_bf16 v[56:59], v[162:165], v[186:189], v[56:59]
	v_mfma_f32_16x16x32_bf16 v[48:51], v[154:157], v[194:197], v[48:51]
	v_mfma_f32_16x16x32_bf16 v[40:43], v[162:165], v[194:197], v[40:43]
	v_mfma_f32_16x16x32_bf16 v[28:31], v[154:157], v[202:205], v[28:31]
	v_mfma_f32_16x16x32_bf16 v[24:27], v[162:165], v[202:205], v[24:27]
	v_mfma_f32_16x16x32_bf16 v[16:19], v[154:157], v[210:213], v[16:19]
	v_mfma_f32_16x16x32_bf16 v[8:11], v[162:165], v[210:213], v[8:11]
	v_mfma_f32_16x16x32_bf16 v[52:55], v[166:169], v[182:185], v[52:55]
	v_mfma_f32_16x16x32_bf16 v[44:47], v[174:177], v[182:185], v[44:47]
	v_mfma_f32_16x16x32_bf16 v[36:39], v[166:169], v[190:193], v[36:39]
	v_mfma_f32_16x16x32_bf16 v[32:35], v[174:177], v[190:193], v[32:35]
	v_mfma_f32_16x16x32_bf16 v[20:23], v[166:169], v[198:201], v[20:23]
	v_mfma_f32_16x16x32_bf16 v[12:15], v[174:177], v[198:201], v[12:15]
	v_mfma_f32_16x16x32_bf16 v[4:7], v[166:169], v[206:209], v[4:7]
	v_mfma_f32_16x16x32_bf16 v[0:3], v[174:177], v[206:209], v[0:3]
	v_mfma_f32_16x16x32_bf16 v[52:55], v[170:173], v[186:189], v[52:55]
	v_mfma_f32_16x16x32_bf16 v[44:47], v[178:181], v[186:189], v[44:47]
	v_mfma_f32_16x16x32_bf16 v[36:39], v[170:173], v[194:197], v[36:39]
	v_mfma_f32_16x16x32_bf16 v[32:35], v[178:181], v[194:197], v[32:35]
	v_mfma_f32_16x16x32_bf16 v[20:23], v[170:173], v[202:205], v[20:23]
	v_mfma_f32_16x16x32_bf16 v[12:15], v[178:181], v[202:205], v[12:15]
	v_mfma_f32_16x16x32_bf16 v[4:7], v[170:173], v[210:213], v[4:7]
	v_mfma_f32_16x16x32_bf16 v[0:3], v[178:181], v[210:213], v[0:3]
	s_setprio 0
	s_barrier
	s_add_i32 s59, s59, 2
	s_add_u32 s6, s6, 0x100
	s_addc_u32 s7, s7, 0
	s_add_u32 s57, s57, 0x100
	s_addc_u32 s58, s58, 0
	s_cmp_gt_u32 s59, 61
	s_cbranch_scc0 .LBB0_2141
	s_and_b64 vcc, exec, s[16:17]
	s_cbranch_vccz .LBB0_2144
	s_barrier
